# layer-0 out-proj residual epilogue de-serialised: x_prompt rows loaded four pieces at a time, two rows in flight, counted waits (was 32 load-wait-store steps)
# speedup vs baseline: 1.0085x; 1.0075x over previous
.LBB0_1251:
	v_lshl_or_b32 v154, s0, 8, v202
	v_lshl_add_u32 v156, s6, 8, v184
	s_mov_b64 s[54:55], -1
	s_cmp_lt_i32 s4, 0
	v_ashrrev_i32_e32 v155, 31, v154
	s_cbranch_scc0 .LBB0_1258
	v_lshl_add_u64 v[132:133], v[154:155], 2, s[14:15]
	global_load_dwordx4 v[144:147], v[132:133], off
	global_load_dwordx4 v[140:143], v[132:133], off offset:64
	global_load_dwordx4 v[136:139], v[132:133], off offset:512
	s_nop 0
	global_load_dwordx4 v[132:135], v[132:133], off offset:576
	v_or_b32_e32 v166, 16, v156
	v_or_b32_e32 v162, 32, v156
	v_or_b32_e32 v160, 48, v156
	s_andn2_b64 vcc, exec, s[18:19]
	v_lshlrev_b64 v[158:159], 1, v[154:155]
	v_ashrrev_i32_e32 v167, 31, v166
	v_ashrrev_i32_e32 v163, 31, v162
	v_ashrrev_i32_e32 v161, 31, v160
	s_cbranch_vccnz .LBB0_1254
	v_ashrrev_i32_e32 v157, 31, v156
	v_lshl_add_u64 v[208:209], s[84:85], 0, v[158:159]
	s_mov_b32 s54, s80
	s_mov_b64 s[56:57], s[82:83]
	s_mov_b64 s[58:59], s[84:85]
	s_mov_b64 vcc, s[86:87]
	s_mov_b32 s39, s81
	v_readlane_b32 s72, v253, 11
	v_readlane_b32 s73, v253, 12
	v_readlane_b32 s84, v253, 23
	v_readlane_b32 s85, v253, 24
	v_lshlrev_b64 v[164:165], 2, v[154:155]
	v_lshl_add_u64 v[164:165], s[72:73], 0, v[164:165]
	v_lshlrev_b64 v[176:177], 13, v[156:157]
	v_lshlrev_b64 v[172:173], 12, v[156:157]
	v_lshl_add_u64 v[176:177], v[176:177], 0, v[164:165]
	v_lshl_add_u64 v[172:173], v[172:173], 0, v[208:209]
	global_load_dwordx4 v[180:183], v[176:177], off offset:64
	global_load_dwordx4 v[186:189], v[176:177], off offset:512
	global_load_dwordx4 v[190:193], v[176:177], off offset:576
	global_load_dwordx4 v[176:179], v[176:177], off
	s_mov_b64 s[84:85], s[58:59]
	v_readlane_b32 s76, v253, 15
	v_readlane_b32 s77, v253, 16
	v_readlane_b32 s74, v253, 13
	v_readlane_b32 s75, v253, 14
	v_readlane_b32 s78, v253, 17
	v_readlane_b32 s79, v253, 18
	v_readlane_b32 s80, v253, 19
	v_readlane_b32 s81, v253, 20
	v_readlane_b32 s82, v253, 21
	v_readlane_b32 s83, v253, 22
	v_readlane_b32 s86, v253, 25
	v_readlane_b32 s87, v253, 26
	v_readlane_b32 s76, v253, 43
	s_mov_b32 s81, s39
	s_mov_b64 s[86:87], vcc
	s_mov_b64 s[82:83], s[56:57]
	s_mov_b32 s80, s54
	v_readlane_b32 s75, v253, 48
	v_readlane_b32 s74, v253, 47
	v_readlane_b32 s79, v253, 46
	v_readlane_b32 s78, v253, 45
	v_readlane_b32 s77, v253, 44
	s_mov_b64 s[54:55], 0
	v_lshlrev_b64 v[194:195], 13, v[166:167]
	v_lshlrev_b64 v[174:175], 12, v[166:167]
	v_lshl_add_u64 v[194:195], v[194:195], 0, v[164:165]
	v_lshl_add_u64 v[174:175], v[174:175], 0, v[208:209]
	global_load_dwordx4 v[198:201], v[194:195], off offset:64
	global_load_dwordx4 v[204:207], v[194:195], off offset:512
	global_load_dwordx4 v[168:171], v[194:195], off offset:576
	global_load_dwordx4 v[194:197], v[194:195], off
	s_waitcnt vmcnt(4)
	v_pk_fma_f32 v[178:179], v[130:131], v[146:147], v[178:179]
	v_pk_fma_f32 v[176:177], v[128:129], v[144:145], v[176:177]
	v_cvt_pk_f16_f32 v179, v178, v179
	v_cvt_pk_f16_f32 v178, v176, v177
	global_store_dwordx2 v[172:173], v[178:179], off
	v_pk_fma_f32 v[182:183], v[126:127], v[142:143], v[182:183]
	v_pk_fma_f32 v[180:181], v[124:125], v[140:141], v[180:181]
	v_cvt_pk_f16_f32 v183, v182, v183
	v_cvt_pk_f16_f32 v182, v180, v181
	global_store_dwordx2 v[172:173], v[182:183], off offset:32
	v_pk_fma_f32 v[188:189], v[98:99], v[138:139], v[188:189]
	v_pk_fma_f32 v[186:187], v[96:97], v[136:137], v[186:187]
	v_cvt_pk_f16_f32 v189, v188, v189
	v_cvt_pk_f16_f32 v188, v186, v187
	global_store_dwordx2 v[172:173], v[188:189], off offset:256
	v_pk_fma_f32 v[192:193], v[94:95], v[134:135], v[192:193]
	v_pk_fma_f32 v[190:191], v[92:93], v[132:133], v[190:191]
	v_cvt_pk_f16_f32 v193, v192, v193
	v_cvt_pk_f16_f32 v192, v190, v191
	global_store_dwordx2 v[172:173], v[192:193], off offset:288
	v_lshlrev_b64 v[176:177], 13, v[162:163]
	v_lshlrev_b64 v[172:173], 12, v[162:163]
	v_lshl_add_u64 v[176:177], v[176:177], 0, v[164:165]
	v_lshl_add_u64 v[172:173], v[172:173], 0, v[208:209]
	global_load_dwordx4 v[180:183], v[176:177], off offset:64
	global_load_dwordx4 v[186:189], v[176:177], off offset:512
	global_load_dwordx4 v[190:193], v[176:177], off offset:576
	global_load_dwordx4 v[176:179], v[176:177], off
	s_waitcnt vmcnt(8)
	v_pk_fma_f32 v[196:197], v[122:123], v[146:147], v[196:197]
	v_pk_fma_f32 v[194:195], v[120:121], v[144:145], v[194:195]
	v_cvt_pk_f16_f32 v197, v196, v197
	v_cvt_pk_f16_f32 v196, v194, v195
	global_store_dwordx2 v[174:175], v[196:197], off
	v_pk_fma_f32 v[200:201], v[118:119], v[142:143], v[200:201]
	v_pk_fma_f32 v[198:199], v[116:117], v[140:141], v[198:199]
	v_cvt_pk_f16_f32 v201, v200, v201
	v_cvt_pk_f16_f32 v200, v198, v199
	global_store_dwordx2 v[174:175], v[200:201], off offset:32
	v_pk_fma_f32 v[206:207], v[90:91], v[138:139], v[206:207]
	v_pk_fma_f32 v[204:205], v[88:89], v[136:137], v[204:205]
	v_cvt_pk_f16_f32 v207, v206, v207
	v_cvt_pk_f16_f32 v206, v204, v205
	global_store_dwordx2 v[174:175], v[206:207], off offset:256
	v_pk_fma_f32 v[170:171], v[86:87], v[134:135], v[170:171]
	v_pk_fma_f32 v[168:169], v[84:85], v[132:133], v[168:169]
	v_cvt_pk_f16_f32 v171, v170, v171
	v_cvt_pk_f16_f32 v170, v168, v169
	global_store_dwordx2 v[174:175], v[170:171], off offset:288
	v_lshlrev_b64 v[194:195], 13, v[160:161]
	v_lshlrev_b64 v[174:175], 12, v[160:161]
	v_lshl_add_u64 v[194:195], v[194:195], 0, v[164:165]
	v_lshl_add_u64 v[174:175], v[174:175], 0, v[208:209]
	global_load_dwordx4 v[198:201], v[194:195], off offset:64
	global_load_dwordx4 v[204:207], v[194:195], off offset:512
	global_load_dwordx4 v[168:171], v[194:195], off offset:576
	global_load_dwordx4 v[194:197], v[194:195], off
	s_waitcnt vmcnt(8)
	v_pk_fma_f32 v[178:179], v[114:115], v[146:147], v[178:179]
	v_pk_fma_f32 v[176:177], v[112:113], v[144:145], v[176:177]
	v_cvt_pk_f16_f32 v179, v178, v179
	v_cvt_pk_f16_f32 v178, v176, v177
	global_store_dwordx2 v[172:173], v[178:179], off
	v_pk_fma_f32 v[182:183], v[110:111], v[142:143], v[182:183]
	v_pk_fma_f32 v[180:181], v[108:109], v[140:141], v[180:181]
	v_cvt_pk_f16_f32 v183, v182, v183
	v_cvt_pk_f16_f32 v182, v180, v181
	global_store_dwordx2 v[172:173], v[182:183], off offset:32
	v_pk_fma_f32 v[188:189], v[82:83], v[138:139], v[188:189]
	v_pk_fma_f32 v[186:187], v[80:81], v[136:137], v[186:187]
	v_cvt_pk_f16_f32 v189, v188, v189
	v_cvt_pk_f16_f32 v188, v186, v187
	global_store_dwordx2 v[172:173], v[188:189], off offset:256
	v_pk_fma_f32 v[192:193], v[78:79], v[134:135], v[192:193]
	v_pk_fma_f32 v[190:191], v[76:77], v[132:133], v[190:191]
	v_cvt_pk_f16_f32 v193, v192, v193
	v_cvt_pk_f16_f32 v192, v190, v191
	global_store_dwordx2 v[172:173], v[192:193], off offset:288
	v_add_u32_e32 v180, 0x80, v156
	v_ashrrev_i32_e32 v181, 31, v180
	v_lshlrev_b64 v[176:177], 13, v[180:181]
	v_lshlrev_b64 v[172:173], 12, v[180:181]
	v_lshl_add_u64 v[176:177], v[176:177], 0, v[164:165]
	v_lshl_add_u64 v[172:173], v[172:173], 0, v[208:209]
	global_load_dwordx4 v[180:183], v[176:177], off offset:64
	global_load_dwordx4 v[186:189], v[176:177], off offset:512
	global_load_dwordx4 v[190:193], v[176:177], off offset:576
	global_load_dwordx4 v[176:179], v[176:177], off
	s_waitcnt vmcnt(8)
	v_pk_fma_f32 v[196:197], v[106:107], v[146:147], v[196:197]
	v_pk_fma_f32 v[194:195], v[104:105], v[144:145], v[194:195]
	v_cvt_pk_f16_f32 v197, v196, v197
	v_cvt_pk_f16_f32 v196, v194, v195
	global_store_dwordx2 v[174:175], v[196:197], off
	v_pk_fma_f32 v[200:201], v[102:103], v[142:143], v[200:201]
	v_pk_fma_f32 v[198:199], v[100:101], v[140:141], v[198:199]
	v_cvt_pk_f16_f32 v201, v200, v201
	v_cvt_pk_f16_f32 v200, v198, v199
	global_store_dwordx2 v[174:175], v[200:201], off offset:32
	v_pk_fma_f32 v[206:207], v[74:75], v[138:139], v[206:207]
	v_pk_fma_f32 v[204:205], v[72:73], v[136:137], v[204:205]
	v_cvt_pk_f16_f32 v207, v206, v207
	v_cvt_pk_f16_f32 v206, v204, v205
	global_store_dwordx2 v[174:175], v[206:207], off offset:256
	v_pk_fma_f32 v[170:171], v[70:71], v[134:135], v[170:171]
	v_pk_fma_f32 v[168:169], v[68:69], v[132:133], v[168:169]
	v_cvt_pk_f16_f32 v171, v170, v171
	v_cvt_pk_f16_f32 v170, v168, v169
	global_store_dwordx2 v[174:175], v[170:171], off offset:288
	v_add_u32_e32 v198, 0x90, v156
	v_ashrrev_i32_e32 v199, 31, v198
	v_lshlrev_b64 v[194:195], 13, v[198:199]
	v_lshlrev_b64 v[174:175], 12, v[198:199]
	v_lshl_add_u64 v[194:195], v[194:195], 0, v[164:165]
	v_lshl_add_u64 v[174:175], v[174:175], 0, v[208:209]
	global_load_dwordx4 v[198:201], v[194:195], off offset:64
	global_load_dwordx4 v[204:207], v[194:195], off offset:512
	global_load_dwordx4 v[168:171], v[194:195], off offset:576
	global_load_dwordx4 v[194:197], v[194:195], off
	s_waitcnt vmcnt(8)
	v_pk_fma_f32 v[178:179], v[66:67], v[146:147], v[178:179]
	v_pk_fma_f32 v[176:177], v[64:65], v[144:145], v[176:177]
	v_cvt_pk_f16_f32 v179, v178, v179
	v_cvt_pk_f16_f32 v178, v176, v177
	global_store_dwordx2 v[172:173], v[178:179], off
	v_pk_fma_f32 v[182:183], v[62:63], v[142:143], v[182:183]
	v_pk_fma_f32 v[180:181], v[60:61], v[140:141], v[180:181]
	v_cvt_pk_f16_f32 v183, v182, v183
	v_cvt_pk_f16_f32 v182, v180, v181
	global_store_dwordx2 v[172:173], v[182:183], off offset:32
	v_pk_fma_f32 v[188:189], v[32:33], v[138:139], v[188:189]
	v_pk_fma_f32 v[186:187], v[30:31], v[136:137], v[186:187]
	v_cvt_pk_f16_f32 v189, v188, v189
	v_cvt_pk_f16_f32 v188, v186, v187
	global_store_dwordx2 v[172:173], v[188:189], off offset:256
	v_pk_fma_f32 v[192:193], v[28:29], v[134:135], v[192:193]
	v_pk_fma_f32 v[190:191], v[26:27], v[132:133], v[190:191]
	v_cvt_pk_f16_f32 v193, v192, v193
	v_cvt_pk_f16_f32 v192, v190, v191
	global_store_dwordx2 v[172:173], v[192:193], off offset:288
	v_add_u32_e32 v180, 0xa0, v156
	v_ashrrev_i32_e32 v181, 31, v180
	v_lshlrev_b64 v[176:177], 13, v[180:181]
	v_lshlrev_b64 v[172:173], 12, v[180:181]
	v_lshl_add_u64 v[176:177], v[176:177], 0, v[164:165]
	v_lshl_add_u64 v[172:173], v[172:173], 0, v[208:209]
	global_load_dwordx4 v[180:183], v[176:177], off offset:64
	global_load_dwordx4 v[186:189], v[176:177], off offset:512
	global_load_dwordx4 v[190:193], v[176:177], off offset:576
	global_load_dwordx4 v[176:179], v[176:177], off
	s_waitcnt vmcnt(8)
	v_pk_fma_f32 v[196:197], v[58:59], v[146:147], v[196:197]
	v_pk_fma_f32 v[194:195], v[56:57], v[144:145], v[194:195]
	v_cvt_pk_f16_f32 v197, v196, v197
	v_cvt_pk_f16_f32 v196, v194, v195
	global_store_dwordx2 v[174:175], v[196:197], off
	v_pk_fma_f32 v[200:201], v[54:55], v[142:143], v[200:201]
	v_pk_fma_f32 v[198:199], v[52:53], v[140:141], v[198:199]
	v_cvt_pk_f16_f32 v201, v200, v201
	v_cvt_pk_f16_f32 v200, v198, v199
	global_store_dwordx2 v[174:175], v[200:201], off offset:32
	v_pk_fma_f32 v[206:207], v[24:25], v[138:139], v[206:207]
	v_pk_fma_f32 v[204:205], v[22:23], v[136:137], v[204:205]
	v_cvt_pk_f16_f32 v207, v206, v207
	v_cvt_pk_f16_f32 v206, v204, v205
	global_store_dwordx2 v[174:175], v[206:207], off offset:256
	v_pk_fma_f32 v[170:171], v[20:21], v[134:135], v[170:171]
	v_pk_fma_f32 v[168:169], v[18:19], v[132:133], v[168:169]
	v_cvt_pk_f16_f32 v171, v170, v171
	v_cvt_pk_f16_f32 v170, v168, v169
	global_store_dwordx2 v[174:175], v[170:171], off offset:288
	v_add_u32_e32 v198, 0xb0, v156
	v_ashrrev_i32_e32 v199, 31, v198
	v_lshlrev_b64 v[194:195], 13, v[198:199]
	v_lshlrev_b64 v[174:175], 12, v[198:199]
	v_lshl_add_u64 v[194:195], v[194:195], 0, v[164:165]
	v_lshl_add_u64 v[174:175], v[174:175], 0, v[208:209]
	global_load_dwordx4 v[198:201], v[194:195], off offset:64
	global_load_dwordx4 v[204:207], v[194:195], off offset:512
	global_load_dwordx4 v[168:171], v[194:195], off offset:576
	global_load_dwordx4 v[194:197], v[194:195], off
	s_waitcnt vmcnt(8)
	v_pk_fma_f32 v[178:179], v[50:51], v[146:147], v[178:179]
	v_pk_fma_f32 v[176:177], v[48:49], v[144:145], v[176:177]
	v_cvt_pk_f16_f32 v179, v178, v179
	v_cvt_pk_f16_f32 v178, v176, v177
	global_store_dwordx2 v[172:173], v[178:179], off
	v_pk_fma_f32 v[182:183], v[46:47], v[142:143], v[182:183]
	v_pk_fma_f32 v[180:181], v[44:45], v[140:141], v[180:181]
	v_cvt_pk_f16_f32 v183, v182, v183
	v_cvt_pk_f16_f32 v182, v180, v181
	global_store_dwordx2 v[172:173], v[182:183], off offset:32
	v_pk_fma_f32 v[188:189], v[16:17], v[138:139], v[188:189]
	v_pk_fma_f32 v[186:187], v[14:15], v[136:137], v[186:187]
	v_cvt_pk_f16_f32 v189, v188, v189
	v_cvt_pk_f16_f32 v188, v186, v187
	global_store_dwordx2 v[172:173], v[188:189], off offset:256
	v_pk_fma_f32 v[192:193], v[12:13], v[134:135], v[192:193]
	v_pk_fma_f32 v[190:191], v[10:11], v[132:133], v[190:191]
	v_cvt_pk_f16_f32 v193, v192, v193
	v_cvt_pk_f16_f32 v192, v190, v191
	global_store_dwordx2 v[172:173], v[192:193], off offset:288
	s_waitcnt vmcnt(4)
	v_pk_fma_f32 v[196:197], v[42:43], v[146:147], v[196:197]
	v_pk_fma_f32 v[194:195], v[40:41], v[144:145], v[194:195]
	v_cvt_pk_f16_f32 v197, v196, v197
	v_cvt_pk_f16_f32 v196, v194, v195
	global_store_dwordx2 v[174:175], v[196:197], off
	v_pk_fma_f32 v[200:201], v[38:39], v[142:143], v[200:201]
	v_pk_fma_f32 v[198:199], v[36:37], v[140:141], v[198:199]
	v_cvt_pk_f16_f32 v201, v200, v201
	v_cvt_pk_f16_f32 v200, v198, v199
	global_store_dwordx2 v[174:175], v[200:201], off offset:32
	v_pk_fma_f32 v[206:207], v[8:9], v[138:139], v[206:207]
	v_pk_fma_f32 v[204:205], v[6:7], v[136:137], v[204:205]
	v_cvt_pk_f16_f32 v207, v206, v207
	v_cvt_pk_f16_f32 v206, v204, v205
	global_store_dwordx2 v[174:175], v[206:207], off offset:256
	v_pk_fma_f32 v[170:171], v[4:5], v[134:135], v[170:171]
	v_pk_fma_f32 v[168:169], v[2:3], v[132:133], v[168:169]
	v_cvt_pk_f16_f32 v171, v170, v171
	v_cvt_pk_f16_f32 v170, v168, v169
	global_store_dwordx2 v[174:175], v[170:171], off offset:288
	s_mov_b32 s73, 0xa000
	s_movk_i32 s72, 0x4000
